# up-GEMM fused FFN epilogue (conv+gelu*val) rewritten by hand: DPP folded into multiplies, packed f32 math, 16-byte ACT stores, constants for both column quads loaded once
# speedup vs baseline: 1.0172x; 1.0143x over previous
.LBB0_1531:
	s_or_b64 exec, exec, s[4:5]
	s_waitcnt lgkmcnt(0)
	s_andn2_b64 vcc, exec, s[58:59]
	s_barrier
	s_cbranch_vccnz .LBB0_1539
	v_lshlrev_b64 v[194:195], 2, v[160:161]
	v_lshl_add_u64 v[162:163], s[18:19], 0, v[194:195]
	global_load_dwordx4 v[196:199], v[162:163], off
	global_load_dwordx4 v[200:203], v[162:163], off offset:16
	v_lshl_add_u64 v[250:251], s[24:25], 0, v[194:195]
	global_load_dwordx4 v[204:207], v[250:251], off
	global_load_dwordx4 v[208:211], v[250:251], off offset:16
	v_lshl_add_u64 v[162:163], s[26:27], 0, v[194:195]
	global_load_dwordx4 v[212:215], v[162:163], off
	global_load_dwordx4 v[216:219], v[162:163], off offset:16
	v_lshl_add_u64 v[250:251], s[6:7], 0, v[194:195]
	global_load_dwordx4 v[220:223], v[250:251], off
	global_load_dwordx4 v[224:227], v[250:251], off offset:16
	v_cmp_eq_u32_e32 vcc, 15, v166
	s_add_i32 s37, 0, 0x20400
	s_nop 1
	v_cndmask_b32_e64 v188, 0, 1, vcc
	v_or_b32_e32 v194, s73, v188
	v_or_b32_e32 v195, s72, v188
	v_lshlrev_b32_e32 v194, 9, v194
	v_lshlrev_b32_e32 v195, 9, v195
	v_add3_u32 v194, s37, v194, v189
	v_add3_u32 v195, s37, v195, v189
	ds_read_b128 v[228:231], v194
	ds_read_b128 v[236:239], v194 offset:16
	ds_read_b128 v[240:243], v195
	ds_read_b128 v[244:247], v195 offset:16
	v_add_u32_e32 v188, s20, v166
	s_lshl_b32 s37, s56, 8
	v_add_u32_e32 v194, s37, v188
	v_ashrrev_i32_e32 v195, 31, v194
	v_lshlrev_b64 v[194:195], 13, v[194:195]
	v_lshl_add_u64 v[162:163], s[14:15], 0, v[194:195]
	v_lshl_add_u64 v[162:163], v[160:161], 1, v[162:163]
	v_cmp_lt_i32_e32 vcc, 1, v166
	s_xor_b64 s[58:59], s[22:23], -1
	s_mov_b64 s[2:3], 0x20000
	s_mov_b64 s[4:5], 0xa0000
	v_mov_b32_e32 v232, 0x3dd2d3e7
	v_mov_b32_e32 v248, 1.0
	s_nop 1
	s_or_b64 s[58:59], s[58:59], vcc
	s_waitcnt vmcnt(0) lgkmcnt(0)
	v_mul_f32_dpp v122, v228, v204 row_ror:1 row_mask:0xf bank_mask:0xf
	v_mul_f32_dpp v168, v236, v208 row_ror:1 row_mask:0xf bank_mask:0xf
	v_mul_f32_dpp v126, v228, v196 row_ror:2 row_mask:0xf bank_mask:0xf
	v_mul_f32_dpp v172, v236, v200 row_ror:2 row_mask:0xf bank_mask:0xf
	v_mul_f32_dpp v123, v229, v205 row_ror:1 row_mask:0xf bank_mask:0xf
	v_mul_f32_dpp v169, v237, v209 row_ror:1 row_mask:0xf bank_mask:0xf
	v_mul_f32_dpp v127, v229, v197 row_ror:2 row_mask:0xf bank_mask:0xf
	v_mul_f32_dpp v173, v237, v201 row_ror:2 row_mask:0xf bank_mask:0xf
	v_mul_f32_dpp v124, v230, v206 row_ror:1 row_mask:0xf bank_mask:0xf
	v_mul_f32_dpp v170, v238, v210 row_ror:1 row_mask:0xf bank_mask:0xf
	v_mul_f32_dpp v128, v230, v198 row_ror:2 row_mask:0xf bank_mask:0xf
	v_mul_f32_dpp v174, v238, v202 row_ror:2 row_mask:0xf bank_mask:0xf
	v_mul_f32_dpp v125, v231, v207 row_ror:1 row_mask:0xf bank_mask:0xf
	v_mul_f32_dpp v171, v239, v211 row_ror:1 row_mask:0xf bank_mask:0xf
	v_mul_f32_dpp v129, v231, v199 row_ror:2 row_mask:0xf bank_mask:0xf
	v_mul_f32_dpp v175, v239, v203 row_ror:2 row_mask:0xf bank_mask:0xf
	v_pk_fma_f32 v[118:119], v[212:213], v[138:139], v[220:221]
	v_pk_fma_f32 v[164:165], v[216:217], v[52:53], v[224:225]
	v_pk_fma_f32 v[120:121], v[214:215], v[140:141], v[222:223]
	v_pk_fma_f32 v[166:167], v[218:219], v[54:55], v[226:227]
	v_mul_f32_dpp v122, v138, v204 row_shr:1 row_mask:0xf bank_mask:0xf
	v_mul_f32_dpp v168, v52, v208 row_shr:1 row_mask:0xf bank_mask:0xf
	v_mul_f32_dpp v126, v138, v196 row_shr:2 row_mask:0xf bank_mask:0xf
	v_mul_f32_dpp v172, v52, v200 row_shr:2 row_mask:0xf bank_mask:0xf
	v_mul_f32_dpp v123, v139, v205 row_shr:1 row_mask:0xf bank_mask:0xf
	v_mul_f32_dpp v169, v53, v209 row_shr:1 row_mask:0xf bank_mask:0xf
	v_mul_f32_dpp v127, v139, v197 row_shr:2 row_mask:0xf bank_mask:0xf
	v_mul_f32_dpp v173, v53, v201 row_shr:2 row_mask:0xf bank_mask:0xf
	v_mul_f32_dpp v124, v140, v206 row_shr:1 row_mask:0xf bank_mask:0xf
	v_mul_f32_dpp v170, v54, v210 row_shr:1 row_mask:0xf bank_mask:0xf
	v_mul_f32_dpp v128, v140, v198 row_shr:2 row_mask:0xf bank_mask:0xf
	v_mul_f32_dpp v174, v54, v202 row_shr:2 row_mask:0xf bank_mask:0xf
	v_mul_f32_dpp v125, v141, v207 row_shr:1 row_mask:0xf bank_mask:0xf
	v_mul_f32_dpp v171, v55, v211 row_shr:1 row_mask:0xf bank_mask:0xf
	v_mul_f32_dpp v129, v141, v199 row_shr:2 row_mask:0xf bank_mask:0xf
	v_mul_f32_dpp v175, v55, v203 row_shr:2 row_mask:0xf bank_mask:0xf
	v_pk_add_f32 v[118:119], v[118:119], v[122:123]
	v_pk_add_f32 v[164:165], v[164:165], v[168:169]
	v_pk_add_f32 v[120:121], v[120:121], v[124:125]
	v_pk_add_f32 v[166:167], v[166:167], v[170:171]
	v_pk_add_f32 v[118:119], v[118:119], v[126:127]
	v_pk_add_f32 v[164:165], v[164:165], v[172:173]
	v_pk_add_f32 v[120:121], v[120:121], v[128:129]
	v_pk_add_f32 v[166:167], v[166:167], v[174:175]
	v_pk_mul_f32 v[122:123], v[118:119], v[118:119]
	v_pk_mul_f32 v[168:169], v[164:165], v[164:165]
	v_pk_mul_f32 v[124:125], v[120:121], v[120:121]
	v_pk_mul_f32 v[170:171], v[166:167], v[166:167]
	v_pk_fma_f32 v[122:123], v[122:123], v[232:233], v[178:179] op_sel_hi:[1,0,0]
	v_pk_fma_f32 v[168:169], v[168:169], v[232:233], v[178:179] op_sel_hi:[1,0,0]
	v_pk_fma_f32 v[124:125], v[124:125], v[232:233], v[178:179] op_sel_hi:[1,0,0]
	v_pk_fma_f32 v[170:171], v[170:171], v[232:233], v[178:179] op_sel_hi:[1,0,0]
	v_pk_mul_f32 v[122:123], v[118:119], v[122:123] neg_lo:[0,1] neg_hi:[0,1]
	v_pk_mul_f32 v[168:169], v[164:165], v[168:169] neg_lo:[0,1] neg_hi:[0,1]
	v_pk_mul_f32 v[124:125], v[120:121], v[124:125] neg_lo:[0,1] neg_hi:[0,1]
	v_pk_mul_f32 v[170:171], v[166:167], v[170:171] neg_lo:[0,1] neg_hi:[0,1]
	v_exp_f32_e32 v126, v122
	v_exp_f32_e32 v172, v168
	v_exp_f32_e32 v127, v123
	v_exp_f32_e32 v173, v169
	v_exp_f32_e32 v128, v124
	v_exp_f32_e32 v174, v170
	v_exp_f32_e32 v129, v125
	v_exp_f32_e32 v175, v171
	v_pk_add_f32 v[126:127], v[126:127], v[248:249] op_sel_hi:[1,0]
	v_pk_add_f32 v[172:173], v[172:173], v[248:249] op_sel_hi:[1,0]
	v_pk_add_f32 v[128:129], v[128:129], v[248:249] op_sel_hi:[1,0]
	v_pk_add_f32 v[174:175], v[174:175], v[248:249] op_sel_hi:[1,0]
	v_rcp_f32_e32 v126, v126
	v_rcp_f32_e32 v172, v172
	v_rcp_f32_e32 v127, v127
	v_rcp_f32_e32 v173, v173
	v_rcp_f32_e32 v128, v128
	v_rcp_f32_e32 v174, v174
	v_rcp_f32_e32 v129, v129
	v_rcp_f32_e32 v175, v175
	v_pk_mul_f32 v[122:123], v[118:119], v[126:127]
	v_pk_mul_f32 v[168:169], v[164:165], v[172:173]
	v_pk_mul_f32 v[124:125], v[120:121], v[128:129]
	v_pk_mul_f32 v[170:171], v[166:167], v[174:175]
	v_pk_mul_f32 v[142:143], v[142:143], v[122:123]
	v_pk_mul_f32 v[60:61], v[60:61], v[168:169]
	v_pk_mul_f32 v[144:145], v[144:145], v[124:125]
	v_pk_mul_f32 v[62:63], v[62:63], v[170:171]
	v_cvt_pk_bf16_f32 v130, v142, v143
	v_cvt_pk_bf16_f32 v132, v60, v61
	v_cvt_pk_bf16_f32 v131, v144, v145
	v_cvt_pk_bf16_f32 v133, v62, v63
	s_and_saveexec_b64 s[38:39], s[58:59]
	global_store_dwordx4 v[162:163], v[130:133], off
	s_mov_b64 exec, s[38:39]
	v_lshl_add_u64 v[162:163], v[162:163], 0, s[2:3]
	v_mul_f32_dpp v122, v138, v204 row_ror:1 row_mask:0xf bank_mask:0xf
	v_mul_f32_dpp v168, v52, v208 row_ror:1 row_mask:0xf bank_mask:0xf
	v_mul_f32_dpp v126, v138, v196 row_ror:2 row_mask:0xf bank_mask:0xf
	v_mul_f32_dpp v172, v52, v200 row_ror:2 row_mask:0xf bank_mask:0xf
	v_mul_f32_dpp v123, v139, v205 row_ror:1 row_mask:0xf bank_mask:0xf
	v_mul_f32_dpp v169, v53, v209 row_ror:1 row_mask:0xf bank_mask:0xf
	v_mul_f32_dpp v127, v139, v197 row_ror:2 row_mask:0xf bank_mask:0xf
	v_mul_f32_dpp v173, v53, v201 row_ror:2 row_mask:0xf bank_mask:0xf
	v_mul_f32_dpp v124, v140, v206 row_ror:1 row_mask:0xf bank_mask:0xf
	v_mul_f32_dpp v170, v54, v210 row_ror:1 row_mask:0xf bank_mask:0xf
	v_mul_f32_dpp v128, v140, v198 row_ror:2 row_mask:0xf bank_mask:0xf
	v_mul_f32_dpp v174, v54, v202 row_ror:2 row_mask:0xf bank_mask:0xf
	v_mul_f32_dpp v125, v141, v207 row_ror:1 row_mask:0xf bank_mask:0xf
	v_mul_f32_dpp v171, v55, v211 row_ror:1 row_mask:0xf bank_mask:0xf
	v_mul_f32_dpp v129, v141, v199 row_ror:2 row_mask:0xf bank_mask:0xf
	v_mul_f32_dpp v175, v55, v203 row_ror:2 row_mask:0xf bank_mask:0xf
	v_pk_fma_f32 v[118:119], v[212:213], v[114:115], v[220:221]
	v_pk_fma_f32 v[164:165], v[216:217], v[48:49], v[224:225]
	v_pk_fma_f32 v[120:121], v[214:215], v[116:117], v[222:223]
	v_pk_fma_f32 v[166:167], v[218:219], v[50:51], v[226:227]
	v_mul_f32_dpp v122, v114, v204 row_shr:1 row_mask:0xf bank_mask:0xf
	v_mul_f32_dpp v168, v48, v208 row_shr:1 row_mask:0xf bank_mask:0xf
	v_mul_f32_dpp v126, v114, v196 row_shr:2 row_mask:0xf bank_mask:0xf
	v_mul_f32_dpp v172, v48, v200 row_shr:2 row_mask:0xf bank_mask:0xf
	v_mul_f32_dpp v123, v115, v205 row_shr:1 row_mask:0xf bank_mask:0xf
	v_mul_f32_dpp v169, v49, v209 row_shr:1 row_mask:0xf bank_mask:0xf
	v_mul_f32_dpp v127, v115, v197 row_shr:2 row_mask:0xf bank_mask:0xf
	v_mul_f32_dpp v173, v49, v201 row_shr:2 row_mask:0xf bank_mask:0xf
	v_mul_f32_dpp v124, v116, v206 row_shr:1 row_mask:0xf bank_mask:0xf
	v_mul_f32_dpp v170, v50, v210 row_shr:1 row_mask:0xf bank_mask:0xf
	v_mul_f32_dpp v128, v116, v198 row_shr:2 row_mask:0xf bank_mask:0xf
	v_mul_f32_dpp v174, v50, v202 row_shr:2 row_mask:0xf bank_mask:0xf
	v_mul_f32_dpp v125, v117, v207 row_shr:1 row_mask:0xf bank_mask:0xf
	v_mul_f32_dpp v171, v51, v211 row_shr:1 row_mask:0xf bank_mask:0xf
	v_mul_f32_dpp v129, v117, v199 row_shr:2 row_mask:0xf bank_mask:0xf
	v_mul_f32_dpp v175, v51, v203 row_shr:2 row_mask:0xf bank_mask:0xf
	v_pk_add_f32 v[118:119], v[118:119], v[122:123]
	v_pk_add_f32 v[164:165], v[164:165], v[168:169]
	v_pk_add_f32 v[120:121], v[120:121], v[124:125]
	v_pk_add_f32 v[166:167], v[166:167], v[170:171]
	v_pk_add_f32 v[118:119], v[118:119], v[126:127]
	v_pk_add_f32 v[164:165], v[164:165], v[172:173]
	v_pk_add_f32 v[120:121], v[120:121], v[128:129]
	v_pk_add_f32 v[166:167], v[166:167], v[174:175]
	v_pk_mul_f32 v[122:123], v[118:119], v[118:119]
	v_pk_mul_f32 v[168:169], v[164:165], v[164:165]
	v_pk_mul_f32 v[124:125], v[120:121], v[120:121]
	v_pk_mul_f32 v[170:171], v[166:167], v[166:167]
	v_pk_fma_f32 v[122:123], v[122:123], v[232:233], v[178:179] op_sel_hi:[1,0,0]
	v_pk_fma_f32 v[168:169], v[168:169], v[232:233], v[178:179] op_sel_hi:[1,0,0]
	v_pk_fma_f32 v[124:125], v[124:125], v[232:233], v[178:179] op_sel_hi:[1,0,0]
	v_pk_fma_f32 v[170:171], v[170:171], v[232:233], v[178:179] op_sel_hi:[1,0,0]
	v_pk_mul_f32 v[122:123], v[118:119], v[122:123] neg_lo:[0,1] neg_hi:[0,1]
	v_pk_mul_f32 v[168:169], v[164:165], v[168:169] neg_lo:[0,1] neg_hi:[0,1]
	v_pk_mul_f32 v[124:125], v[120:121], v[124:125] neg_lo:[0,1] neg_hi:[0,1]
	v_pk_mul_f32 v[170:171], v[166:167], v[170:171] neg_lo:[0,1] neg_hi:[0,1]
	v_exp_f32_e32 v126, v122
	v_exp_f32_e32 v172, v168
	v_exp_f32_e32 v127, v123
	v_exp_f32_e32 v173, v169
	v_exp_f32_e32 v128, v124
	v_exp_f32_e32 v174, v170
	v_exp_f32_e32 v129, v125
	v_exp_f32_e32 v175, v171
	v_pk_add_f32 v[126:127], v[126:127], v[248:249] op_sel_hi:[1,0]
	v_pk_add_f32 v[172:173], v[172:173], v[248:249] op_sel_hi:[1,0]
	v_pk_add_f32 v[128:129], v[128:129], v[248:249] op_sel_hi:[1,0]
	v_pk_add_f32 v[174:175], v[174:175], v[248:249] op_sel_hi:[1,0]
	v_rcp_f32_e32 v126, v126
	v_rcp_f32_e32 v172, v172
	v_rcp_f32_e32 v127, v127
	v_rcp_f32_e32 v173, v173
	v_rcp_f32_e32 v128, v128
	v_rcp_f32_e32 v174, v174
	v_rcp_f32_e32 v129, v129
	v_rcp_f32_e32 v175, v175
	v_pk_mul_f32 v[122:123], v[118:119], v[126:127]
	v_pk_mul_f32 v[168:169], v[164:165], v[172:173]
	v_pk_mul_f32 v[124:125], v[120:121], v[128:129]
	v_pk_mul_f32 v[170:171], v[166:167], v[174:175]
	v_pk_mul_f32 v[134:135], v[134:135], v[122:123]
	v_pk_mul_f32 v[56:57], v[56:57], v[168:169]
	v_pk_mul_f32 v[136:137], v[136:137], v[124:125]
	v_pk_mul_f32 v[58:59], v[58:59], v[170:171]
	v_cvt_pk_bf16_f32 v190, v134, v135
	v_cvt_pk_bf16_f32 v192, v56, v57
	v_cvt_pk_bf16_f32 v191, v136, v137
	v_cvt_pk_bf16_f32 v193, v58, v59
	global_store_dwordx4 v[162:163], v[190:193], off
	v_lshl_add_u64 v[162:163], v[162:163], 0, s[2:3]
	v_mul_f32_dpp v122, v114, v204 row_ror:1 row_mask:0xf bank_mask:0xf
	v_mul_f32_dpp v168, v48, v208 row_ror:1 row_mask:0xf bank_mask:0xf
	v_mul_f32_dpp v126, v114, v196 row_ror:2 row_mask:0xf bank_mask:0xf
	v_mul_f32_dpp v172, v48, v200 row_ror:2 row_mask:0xf bank_mask:0xf
	v_mul_f32_dpp v123, v115, v205 row_ror:1 row_mask:0xf bank_mask:0xf
	v_mul_f32_dpp v169, v49, v209 row_ror:1 row_mask:0xf bank_mask:0xf
	v_mul_f32_dpp v127, v115, v197 row_ror:2 row_mask:0xf bank_mask:0xf
	v_mul_f32_dpp v173, v49, v201 row_ror:2 row_mask:0xf bank_mask:0xf
	v_mul_f32_dpp v124, v116, v206 row_ror:1 row_mask:0xf bank_mask:0xf
	v_mul_f32_dpp v170, v50, v210 row_ror:1 row_mask:0xf bank_mask:0xf
	v_mul_f32_dpp v128, v116, v198 row_ror:2 row_mask:0xf bank_mask:0xf
	v_mul_f32_dpp v174, v50, v202 row_ror:2 row_mask:0xf bank_mask:0xf
	v_mul_f32_dpp v125, v117, v207 row_ror:1 row_mask:0xf bank_mask:0xf
	v_mul_f32_dpp v171, v51, v211 row_ror:1 row_mask:0xf bank_mask:0xf
	v_mul_f32_dpp v129, v117, v199 row_ror:2 row_mask:0xf bank_mask:0xf
	v_mul_f32_dpp v175, v51, v203 row_ror:2 row_mask:0xf bank_mask:0xf
	v_pk_fma_f32 v[118:119], v[212:213], v[106:107], v[220:221]
	v_pk_fma_f32 v[164:165], v[216:217], v[40:41], v[224:225]
	v_pk_fma_f32 v[120:121], v[214:215], v[108:109], v[222:223]
	v_pk_fma_f32 v[166:167], v[218:219], v[42:43], v[226:227]
	v_mul_f32_dpp v122, v106, v204 row_shr:1 row_mask:0xf bank_mask:0xf
	v_mul_f32_dpp v168, v40, v208 row_shr:1 row_mask:0xf bank_mask:0xf
	v_mul_f32_dpp v126, v106, v196 row_shr:2 row_mask:0xf bank_mask:0xf
	v_mul_f32_dpp v172, v40, v200 row_shr:2 row_mask:0xf bank_mask:0xf
	v_mul_f32_dpp v123, v107, v205 row_shr:1 row_mask:0xf bank_mask:0xf
	v_mul_f32_dpp v169, v41, v209 row_shr:1 row_mask:0xf bank_mask:0xf
	v_mul_f32_dpp v127, v107, v197 row_shr:2 row_mask:0xf bank_mask:0xf
	v_mul_f32_dpp v173, v41, v201 row_shr:2 row_mask:0xf bank_mask:0xf
	v_mul_f32_dpp v124, v108, v206 row_shr:1 row_mask:0xf bank_mask:0xf
	v_mul_f32_dpp v170, v42, v210 row_shr:1 row_mask:0xf bank_mask:0xf
	v_mul_f32_dpp v128, v108, v198 row_shr:2 row_mask:0xf bank_mask:0xf
	v_mul_f32_dpp v174, v42, v202 row_shr:2 row_mask:0xf bank_mask:0xf
	v_mul_f32_dpp v125, v109, v207 row_shr:1 row_mask:0xf bank_mask:0xf
	v_mul_f32_dpp v171, v43, v211 row_shr:1 row_mask:0xf bank_mask:0xf
	v_mul_f32_dpp v129, v109, v199 row_shr:2 row_mask:0xf bank_mask:0xf
	v_mul_f32_dpp v175, v43, v203 row_shr:2 row_mask:0xf bank_mask:0xf
	v_pk_add_f32 v[118:119], v[118:119], v[122:123]
	v_pk_add_f32 v[164:165], v[164:165], v[168:169]
	v_pk_add_f32 v[120:121], v[120:121], v[124:125]
	v_pk_add_f32 v[166:167], v[166:167], v[170:171]
	v_pk_add_f32 v[118:119], v[118:119], v[126:127]
	v_pk_add_f32 v[164:165], v[164:165], v[172:173]
	v_pk_add_f32 v[120:121], v[120:121], v[128:129]
	v_pk_add_f32 v[166:167], v[166:167], v[174:175]
	v_pk_mul_f32 v[122:123], v[118:119], v[118:119]
	v_pk_mul_f32 v[168:169], v[164:165], v[164:165]
	v_pk_mul_f32 v[124:125], v[120:121], v[120:121]
	v_pk_mul_f32 v[170:171], v[166:167], v[166:167]
	v_pk_fma_f32 v[122:123], v[122:123], v[232:233], v[178:179] op_sel_hi:[1,0,0]
	v_pk_fma_f32 v[168:169], v[168:169], v[232:233], v[178:179] op_sel_hi:[1,0,0]
	v_pk_fma_f32 v[124:125], v[124:125], v[232:233], v[178:179] op_sel_hi:[1,0,0]
	v_pk_fma_f32 v[170:171], v[170:171], v[232:233], v[178:179] op_sel_hi:[1,0,0]
	v_pk_mul_f32 v[122:123], v[118:119], v[122:123] neg_lo:[0,1] neg_hi:[0,1]
	v_pk_mul_f32 v[168:169], v[164:165], v[168:169] neg_lo:[0,1] neg_hi:[0,1]
	v_pk_mul_f32 v[124:125], v[120:121], v[124:125] neg_lo:[0,1] neg_hi:[0,1]
	v_pk_mul_f32 v[170:171], v[166:167], v[170:171] neg_lo:[0,1] neg_hi:[0,1]
	v_exp_f32_e32 v126, v122
	v_exp_f32_e32 v172, v168
	v_exp_f32_e32 v127, v123
	v_exp_f32_e32 v173, v169
	v_exp_f32_e32 v128, v124
	v_exp_f32_e32 v174, v170
	v_exp_f32_e32 v129, v125
	v_exp_f32_e32 v175, v171
	v_pk_add_f32 v[126:127], v[126:127], v[248:249] op_sel_hi:[1,0]
	v_pk_add_f32 v[172:173], v[172:173], v[248:249] op_sel_hi:[1,0]
	v_pk_add_f32 v[128:129], v[128:129], v[248:249] op_sel_hi:[1,0]
	v_pk_add_f32 v[174:175], v[174:175], v[248:249] op_sel_hi:[1,0]
	v_rcp_f32_e32 v126, v126
	v_rcp_f32_e32 v172, v172
	v_rcp_f32_e32 v127, v127
	v_rcp_f32_e32 v173, v173
	v_rcp_f32_e32 v128, v128
	v_rcp_f32_e32 v174, v174
	v_rcp_f32_e32 v129, v129
	v_rcp_f32_e32 v175, v175
	v_pk_mul_f32 v[122:123], v[118:119], v[126:127]
	v_pk_mul_f32 v[168:169], v[164:165], v[172:173]
	v_pk_mul_f32 v[124:125], v[120:121], v[128:129]
	v_pk_mul_f32 v[170:171], v[166:167], v[174:175]
	v_pk_mul_f32 v[110:111], v[110:111], v[122:123]
	v_pk_mul_f32 v[44:45], v[44:45], v[168:169]
	v_pk_mul_f32 v[112:113], v[112:113], v[124:125]
	v_pk_mul_f32 v[46:47], v[46:47], v[170:171]
	v_cvt_pk_bf16_f32 v130, v110, v111
	v_cvt_pk_bf16_f32 v132, v44, v45
	v_cvt_pk_bf16_f32 v131, v112, v113
	v_cvt_pk_bf16_f32 v133, v46, v47
	global_store_dwordx4 v[162:163], v[130:133], off
	v_lshl_add_u64 v[162:163], v[162:163], 0, s[2:3]
	v_mul_f32_dpp v122, v106, v204 row_ror:1 row_mask:0xf bank_mask:0xf
	v_mul_f32_dpp v168, v40, v208 row_ror:1 row_mask:0xf bank_mask:0xf
	v_mul_f32_dpp v126, v106, v196 row_ror:2 row_mask:0xf bank_mask:0xf
	v_mul_f32_dpp v172, v40, v200 row_ror:2 row_mask:0xf bank_mask:0xf
	v_mul_f32_dpp v123, v107, v205 row_ror:1 row_mask:0xf bank_mask:0xf
	v_mul_f32_dpp v169, v41, v209 row_ror:1 row_mask:0xf bank_mask:0xf
	v_mul_f32_dpp v127, v107, v197 row_ror:2 row_mask:0xf bank_mask:0xf
	v_mul_f32_dpp v173, v41, v201 row_ror:2 row_mask:0xf bank_mask:0xf
	v_mul_f32_dpp v124, v108, v206 row_ror:1 row_mask:0xf bank_mask:0xf
	v_mul_f32_dpp v170, v42, v210 row_ror:1 row_mask:0xf bank_mask:0xf
	v_mul_f32_dpp v128, v108, v198 row_ror:2 row_mask:0xf bank_mask:0xf
	v_mul_f32_dpp v174, v42, v202 row_ror:2 row_mask:0xf bank_mask:0xf
	v_mul_f32_dpp v125, v109, v207 row_ror:1 row_mask:0xf bank_mask:0xf
	v_mul_f32_dpp v171, v43, v211 row_ror:1 row_mask:0xf bank_mask:0xf
	v_mul_f32_dpp v129, v109, v199 row_ror:2 row_mask:0xf bank_mask:0xf
	v_mul_f32_dpp v175, v43, v203 row_ror:2 row_mask:0xf bank_mask:0xf
	v_pk_fma_f32 v[118:119], v[212:213], v[102:103], v[220:221]
	v_pk_fma_f32 v[164:165], v[216:217], v[36:37], v[224:225]
	v_pk_fma_f32 v[120:121], v[214:215], v[104:105], v[222:223]
	v_pk_fma_f32 v[166:167], v[218:219], v[38:39], v[226:227]
	v_mul_f32_dpp v122, v102, v204 row_shr:1 row_mask:0xf bank_mask:0xf
	v_mul_f32_dpp v168, v36, v208 row_shr:1 row_mask:0xf bank_mask:0xf
	v_mul_f32_dpp v126, v102, v196 row_shr:2 row_mask:0xf bank_mask:0xf
	v_mul_f32_dpp v172, v36, v200 row_shr:2 row_mask:0xf bank_mask:0xf
	v_mul_f32_dpp v123, v103, v205 row_shr:1 row_mask:0xf bank_mask:0xf
	v_mul_f32_dpp v169, v37, v209 row_shr:1 row_mask:0xf bank_mask:0xf
	v_mul_f32_dpp v127, v103, v197 row_shr:2 row_mask:0xf bank_mask:0xf
	v_mul_f32_dpp v173, v37, v201 row_shr:2 row_mask:0xf bank_mask:0xf
	v_mul_f32_dpp v124, v104, v206 row_shr:1 row_mask:0xf bank_mask:0xf
	v_mul_f32_dpp v170, v38, v210 row_shr:1 row_mask:0xf bank_mask:0xf
	v_mul_f32_dpp v128, v104, v198 row_shr:2 row_mask:0xf bank_mask:0xf
	v_mul_f32_dpp v174, v38, v202 row_shr:2 row_mask:0xf bank_mask:0xf
	v_mul_f32_dpp v125, v105, v207 row_shr:1 row_mask:0xf bank_mask:0xf
	v_mul_f32_dpp v171, v39, v211 row_shr:1 row_mask:0xf bank_mask:0xf
	v_mul_f32_dpp v129, v105, v199 row_shr:2 row_mask:0xf bank_mask:0xf
	v_mul_f32_dpp v175, v39, v203 row_shr:2 row_mask:0xf bank_mask:0xf
	v_pk_add_f32 v[118:119], v[118:119], v[122:123]
	v_pk_add_f32 v[164:165], v[164:165], v[168:169]
	v_pk_add_f32 v[120:121], v[120:121], v[124:125]
	v_pk_add_f32 v[166:167], v[166:167], v[170:171]
	v_pk_add_f32 v[118:119], v[118:119], v[126:127]
	v_pk_add_f32 v[164:165], v[164:165], v[172:173]
	v_pk_add_f32 v[120:121], v[120:121], v[128:129]
	v_pk_add_f32 v[166:167], v[166:167], v[174:175]
	v_pk_mul_f32 v[122:123], v[118:119], v[118:119]
	v_pk_mul_f32 v[168:169], v[164:165], v[164:165]
	v_pk_mul_f32 v[124:125], v[120:121], v[120:121]
	v_pk_mul_f32 v[170:171], v[166:167], v[166:167]
	v_pk_fma_f32 v[122:123], v[122:123], v[232:233], v[178:179] op_sel_hi:[1,0,0]
	v_pk_fma_f32 v[168:169], v[168:169], v[232:233], v[178:179] op_sel_hi:[1,0,0]
	v_pk_fma_f32 v[124:125], v[124:125], v[232:233], v[178:179] op_sel_hi:[1,0,0]
	v_pk_fma_f32 v[170:171], v[170:171], v[232:233], v[178:179] op_sel_hi:[1,0,0]
	v_pk_mul_f32 v[122:123], v[118:119], v[122:123] neg_lo:[0,1] neg_hi:[0,1]
	v_pk_mul_f32 v[168:169], v[164:165], v[168:169] neg_lo:[0,1] neg_hi:[0,1]
	v_pk_mul_f32 v[124:125], v[120:121], v[124:125] neg_lo:[0,1] neg_hi:[0,1]
	v_pk_mul_f32 v[170:171], v[166:167], v[170:171] neg_lo:[0,1] neg_hi:[0,1]
	v_exp_f32_e32 v126, v122
	v_exp_f32_e32 v172, v168
	v_exp_f32_e32 v127, v123
	v_exp_f32_e32 v173, v169
	v_exp_f32_e32 v128, v124
	v_exp_f32_e32 v174, v170
	v_exp_f32_e32 v129, v125
	v_exp_f32_e32 v175, v171
	v_pk_add_f32 v[126:127], v[126:127], v[248:249] op_sel_hi:[1,0]
	v_pk_add_f32 v[172:173], v[172:173], v[248:249] op_sel_hi:[1,0]
	v_pk_add_f32 v[128:129], v[128:129], v[248:249] op_sel_hi:[1,0]
	v_pk_add_f32 v[174:175], v[174:175], v[248:249] op_sel_hi:[1,0]
	v_rcp_f32_e32 v126, v126
	v_rcp_f32_e32 v172, v172
	v_rcp_f32_e32 v127, v127
	v_rcp_f32_e32 v173, v173
	v_rcp_f32_e32 v128, v128
	v_rcp_f32_e32 v174, v174
	v_rcp_f32_e32 v129, v129
	v_rcp_f32_e32 v175, v175
	v_pk_mul_f32 v[122:123], v[118:119], v[126:127]
	v_pk_mul_f32 v[168:169], v[164:165], v[172:173]
	v_pk_mul_f32 v[124:125], v[120:121], v[128:129]
	v_pk_mul_f32 v[170:171], v[166:167], v[174:175]
	v_pk_mul_f32 v[98:99], v[98:99], v[122:123]
	v_pk_mul_f32 v[32:33], v[32:33], v[168:169]
	v_pk_mul_f32 v[100:101], v[100:101], v[124:125]
	v_pk_mul_f32 v[34:35], v[34:35], v[170:171]
	v_cvt_pk_bf16_f32 v190, v98, v99
	v_cvt_pk_bf16_f32 v192, v32, v33
	v_cvt_pk_bf16_f32 v191, v100, v101
	v_cvt_pk_bf16_f32 v193, v34, v35
	global_store_dwordx4 v[162:163], v[190:193], off
	v_lshl_add_u64 v[162:163], v[162:163], 0, s[4:5]
	v_mul_f32_dpp v122, v240, v204 row_ror:1 row_mask:0xf bank_mask:0xf
	v_mul_f32_dpp v168, v244, v208 row_ror:1 row_mask:0xf bank_mask:0xf
	v_mul_f32_dpp v126, v240, v196 row_ror:2 row_mask:0xf bank_mask:0xf
	v_mul_f32_dpp v172, v244, v200 row_ror:2 row_mask:0xf bank_mask:0xf
	v_mul_f32_dpp v123, v241, v205 row_ror:1 row_mask:0xf bank_mask:0xf
	v_mul_f32_dpp v169, v245, v209 row_ror:1 row_mask:0xf bank_mask:0xf
	v_mul_f32_dpp v127, v241, v197 row_ror:2 row_mask:0xf bank_mask:0xf
	v_mul_f32_dpp v173, v245, v201 row_ror:2 row_mask:0xf bank_mask:0xf
	v_mul_f32_dpp v124, v242, v206 row_ror:1 row_mask:0xf bank_mask:0xf
	v_mul_f32_dpp v170, v246, v210 row_ror:1 row_mask:0xf bank_mask:0xf
	v_mul_f32_dpp v128, v242, v198 row_ror:2 row_mask:0xf bank_mask:0xf
	v_mul_f32_dpp v174, v246, v202 row_ror:2 row_mask:0xf bank_mask:0xf
	v_mul_f32_dpp v125, v243, v207 row_ror:1 row_mask:0xf bank_mask:0xf
	v_mul_f32_dpp v171, v247, v211 row_ror:1 row_mask:0xf bank_mask:0xf
	v_mul_f32_dpp v129, v243, v199 row_ror:2 row_mask:0xf bank_mask:0xf
	v_mul_f32_dpp v175, v247, v203 row_ror:2 row_mask:0xf bank_mask:0xf
	v_pk_fma_f32 v[118:119], v[212:213], v[88:89], v[220:221]
	v_pk_fma_f32 v[164:165], v[216:217], v[24:25], v[224:225]
	v_pk_fma_f32 v[120:121], v[214:215], v[90:91], v[222:223]
	v_pk_fma_f32 v[166:167], v[218:219], v[26:27], v[226:227]
	v_mul_f32_dpp v122, v88, v204 row_shr:1 row_mask:0xf bank_mask:0xf
	v_mul_f32_dpp v168, v24, v208 row_shr:1 row_mask:0xf bank_mask:0xf
	v_mul_f32_dpp v126, v88, v196 row_shr:2 row_mask:0xf bank_mask:0xf
	v_mul_f32_dpp v172, v24, v200 row_shr:2 row_mask:0xf bank_mask:0xf
	v_mul_f32_dpp v123, v89, v205 row_shr:1 row_mask:0xf bank_mask:0xf
	v_mul_f32_dpp v169, v25, v209 row_shr:1 row_mask:0xf bank_mask:0xf
	v_mul_f32_dpp v127, v89, v197 row_shr:2 row_mask:0xf bank_mask:0xf
	v_mul_f32_dpp v173, v25, v201 row_shr:2 row_mask:0xf bank_mask:0xf
	v_mul_f32_dpp v124, v90, v206 row_shr:1 row_mask:0xf bank_mask:0xf
	v_mul_f32_dpp v170, v26, v210 row_shr:1 row_mask:0xf bank_mask:0xf
	v_mul_f32_dpp v128, v90, v198 row_shr:2 row_mask:0xf bank_mask:0xf
	v_mul_f32_dpp v174, v26, v202 row_shr:2 row_mask:0xf bank_mask:0xf
	v_mul_f32_dpp v125, v91, v207 row_shr:1 row_mask:0xf bank_mask:0xf
	v_mul_f32_dpp v171, v27, v211 row_shr:1 row_mask:0xf bank_mask:0xf
	v_mul_f32_dpp v129, v91, v199 row_shr:2 row_mask:0xf bank_mask:0xf
	v_mul_f32_dpp v175, v27, v203 row_shr:2 row_mask:0xf bank_mask:0xf
	v_pk_add_f32 v[118:119], v[118:119], v[122:123]
	v_pk_add_f32 v[164:165], v[164:165], v[168:169]
	v_pk_add_f32 v[120:121], v[120:121], v[124:125]
	v_pk_add_f32 v[166:167], v[166:167], v[170:171]
	v_pk_add_f32 v[118:119], v[118:119], v[126:127]
	v_pk_add_f32 v[164:165], v[164:165], v[172:173]
	v_pk_add_f32 v[120:121], v[120:121], v[128:129]
	v_pk_add_f32 v[166:167], v[166:167], v[174:175]
	v_pk_mul_f32 v[122:123], v[118:119], v[118:119]
	v_pk_mul_f32 v[168:169], v[164:165], v[164:165]
	v_pk_mul_f32 v[124:125], v[120:121], v[120:121]
	v_pk_mul_f32 v[170:171], v[166:167], v[166:167]
	v_pk_fma_f32 v[122:123], v[122:123], v[232:233], v[178:179] op_sel_hi:[1,0,0]
	v_pk_fma_f32 v[168:169], v[168:169], v[232:233], v[178:179] op_sel_hi:[1,0,0]
	v_pk_fma_f32 v[124:125], v[124:125], v[232:233], v[178:179] op_sel_hi:[1,0,0]
	v_pk_fma_f32 v[170:171], v[170:171], v[232:233], v[178:179] op_sel_hi:[1,0,0]
	v_pk_mul_f32 v[122:123], v[118:119], v[122:123] neg_lo:[0,1] neg_hi:[0,1]
	v_pk_mul_f32 v[168:169], v[164:165], v[168:169] neg_lo:[0,1] neg_hi:[0,1]
	v_pk_mul_f32 v[124:125], v[120:121], v[124:125] neg_lo:[0,1] neg_hi:[0,1]
	v_pk_mul_f32 v[170:171], v[166:167], v[170:171] neg_lo:[0,1] neg_hi:[0,1]
	v_exp_f32_e32 v126, v122
	v_exp_f32_e32 v172, v168
	v_exp_f32_e32 v127, v123
	v_exp_f32_e32 v173, v169
	v_exp_f32_e32 v128, v124
	v_exp_f32_e32 v174, v170
	v_exp_f32_e32 v129, v125
	v_exp_f32_e32 v175, v171
	v_pk_add_f32 v[126:127], v[126:127], v[248:249] op_sel_hi:[1,0]
	v_pk_add_f32 v[172:173], v[172:173], v[248:249] op_sel_hi:[1,0]
	v_pk_add_f32 v[128:129], v[128:129], v[248:249] op_sel_hi:[1,0]
	v_pk_add_f32 v[174:175], v[174:175], v[248:249] op_sel_hi:[1,0]
	v_rcp_f32_e32 v126, v126
	v_rcp_f32_e32 v172, v172
	v_rcp_f32_e32 v127, v127
	v_rcp_f32_e32 v173, v173
	v_rcp_f32_e32 v128, v128
	v_rcp_f32_e32 v174, v174
	v_rcp_f32_e32 v129, v129
	v_rcp_f32_e32 v175, v175
	v_pk_mul_f32 v[122:123], v[118:119], v[126:127]
	v_pk_mul_f32 v[168:169], v[164:165], v[172:173]
	v_pk_mul_f32 v[124:125], v[120:121], v[128:129]
	v_pk_mul_f32 v[170:171], v[166:167], v[174:175]
	v_pk_mul_f32 v[92:93], v[92:93], v[122:123]
	v_pk_mul_f32 v[28:29], v[28:29], v[168:169]
	v_pk_mul_f32 v[94:95], v[94:95], v[124:125]
	v_pk_mul_f32 v[30:31], v[30:31], v[170:171]
	v_cvt_pk_bf16_f32 v130, v92, v93
	v_cvt_pk_bf16_f32 v132, v28, v29
	v_cvt_pk_bf16_f32 v131, v94, v95
	v_cvt_pk_bf16_f32 v133, v30, v31
	global_store_dwordx4 v[162:163], v[130:133], off
	v_lshl_add_u64 v[162:163], v[162:163], 0, s[2:3]
	v_mul_f32_dpp v122, v88, v204 row_ror:1 row_mask:0xf bank_mask:0xf
	v_mul_f32_dpp v168, v24, v208 row_ror:1 row_mask:0xf bank_mask:0xf
	v_mul_f32_dpp v126, v88, v196 row_ror:2 row_mask:0xf bank_mask:0xf
	v_mul_f32_dpp v172, v24, v200 row_ror:2 row_mask:0xf bank_mask:0xf
	v_mul_f32_dpp v123, v89, v205 row_ror:1 row_mask:0xf bank_mask:0xf
	v_mul_f32_dpp v169, v25, v209 row_ror:1 row_mask:0xf bank_mask:0xf
	v_mul_f32_dpp v127, v89, v197 row_ror:2 row_mask:0xf bank_mask:0xf
	v_mul_f32_dpp v173, v25, v201 row_ror:2 row_mask:0xf bank_mask:0xf
	v_mul_f32_dpp v124, v90, v206 row_ror:1 row_mask:0xf bank_mask:0xf
	v_mul_f32_dpp v170, v26, v210 row_ror:1 row_mask:0xf bank_mask:0xf
	v_mul_f32_dpp v128, v90, v198 row_ror:2 row_mask:0xf bank_mask:0xf
	v_mul_f32_dpp v174, v26, v202 row_ror:2 row_mask:0xf bank_mask:0xf
	v_mul_f32_dpp v125, v91, v207 row_ror:1 row_mask:0xf bank_mask:0xf
	v_mul_f32_dpp v171, v27, v211 row_ror:1 row_mask:0xf bank_mask:0xf
	v_mul_f32_dpp v129, v91, v199 row_ror:2 row_mask:0xf bank_mask:0xf
	v_mul_f32_dpp v175, v27, v203 row_ror:2 row_mask:0xf bank_mask:0xf
	v_pk_fma_f32 v[118:119], v[212:213], v[80:81], v[220:221]
	v_pk_fma_f32 v[164:165], v[216:217], v[16:17], v[224:225]
	v_pk_fma_f32 v[120:121], v[214:215], v[82:83], v[222:223]
	v_pk_fma_f32 v[166:167], v[218:219], v[18:19], v[226:227]
	v_mul_f32_dpp v122, v80, v204 row_shr:1 row_mask:0xf bank_mask:0xf
	v_mul_f32_dpp v168, v16, v208 row_shr:1 row_mask:0xf bank_mask:0xf
	v_mul_f32_dpp v126, v80, v196 row_shr:2 row_mask:0xf bank_mask:0xf
	v_mul_f32_dpp v172, v16, v200 row_shr:2 row_mask:0xf bank_mask:0xf
	v_mul_f32_dpp v123, v81, v205 row_shr:1 row_mask:0xf bank_mask:0xf
	v_mul_f32_dpp v169, v17, v209 row_shr:1 row_mask:0xf bank_mask:0xf
	v_mul_f32_dpp v127, v81, v197 row_shr:2 row_mask:0xf bank_mask:0xf
	v_mul_f32_dpp v173, v17, v201 row_shr:2 row_mask:0xf bank_mask:0xf
	v_mul_f32_dpp v124, v82, v206 row_shr:1 row_mask:0xf bank_mask:0xf
	v_mul_f32_dpp v170, v18, v210 row_shr:1 row_mask:0xf bank_mask:0xf
	v_mul_f32_dpp v128, v82, v198 row_shr:2 row_mask:0xf bank_mask:0xf
	v_mul_f32_dpp v174, v18, v202 row_shr:2 row_mask:0xf bank_mask:0xf
	v_mul_f32_dpp v125, v83, v207 row_shr:1 row_mask:0xf bank_mask:0xf
	v_mul_f32_dpp v171, v19, v211 row_shr:1 row_mask:0xf bank_mask:0xf
	v_mul_f32_dpp v129, v83, v199 row_shr:2 row_mask:0xf bank_mask:0xf
	v_mul_f32_dpp v175, v19, v203 row_shr:2 row_mask:0xf bank_mask:0xf
	v_pk_add_f32 v[118:119], v[118:119], v[122:123]
	v_pk_add_f32 v[164:165], v[164:165], v[168:169]
	v_pk_add_f32 v[120:121], v[120:121], v[124:125]
	v_pk_add_f32 v[166:167], v[166:167], v[170:171]
	v_pk_add_f32 v[118:119], v[118:119], v[126:127]
	v_pk_add_f32 v[164:165], v[164:165], v[172:173]
	v_pk_add_f32 v[120:121], v[120:121], v[128:129]
	v_pk_add_f32 v[166:167], v[166:167], v[174:175]
	v_pk_mul_f32 v[122:123], v[118:119], v[118:119]
	v_pk_mul_f32 v[168:169], v[164:165], v[164:165]
	v_pk_mul_f32 v[124:125], v[120:121], v[120:121]
	v_pk_mul_f32 v[170:171], v[166:167], v[166:167]
	v_pk_fma_f32 v[122:123], v[122:123], v[232:233], v[178:179] op_sel_hi:[1,0,0]
	v_pk_fma_f32 v[168:169], v[168:169], v[232:233], v[178:179] op_sel_hi:[1,0,0]
	v_pk_fma_f32 v[124:125], v[124:125], v[232:233], v[178:179] op_sel_hi:[1,0,0]
	v_pk_fma_f32 v[170:171], v[170:171], v[232:233], v[178:179] op_sel_hi:[1,0,0]
	v_pk_mul_f32 v[122:123], v[118:119], v[122:123] neg_lo:[0,1] neg_hi:[0,1]
	v_pk_mul_f32 v[168:169], v[164:165], v[168:169] neg_lo:[0,1] neg_hi:[0,1]
	v_pk_mul_f32 v[124:125], v[120:121], v[124:125] neg_lo:[0,1] neg_hi:[0,1]
	v_pk_mul_f32 v[170:171], v[166:167], v[170:171] neg_lo:[0,1] neg_hi:[0,1]
	v_exp_f32_e32 v126, v122
	v_exp_f32_e32 v172, v168
	v_exp_f32_e32 v127, v123
	v_exp_f32_e32 v173, v169
	v_exp_f32_e32 v128, v124
	v_exp_f32_e32 v174, v170
	v_exp_f32_e32 v129, v125
	v_exp_f32_e32 v175, v171
	v_pk_add_f32 v[126:127], v[126:127], v[248:249] op_sel_hi:[1,0]
	v_pk_add_f32 v[172:173], v[172:173], v[248:249] op_sel_hi:[1,0]
	v_pk_add_f32 v[128:129], v[128:129], v[248:249] op_sel_hi:[1,0]
	v_pk_add_f32 v[174:175], v[174:175], v[248:249] op_sel_hi:[1,0]
	v_rcp_f32_e32 v126, v126
	v_rcp_f32_e32 v172, v172
	v_rcp_f32_e32 v127, v127
	v_rcp_f32_e32 v173, v173
	v_rcp_f32_e32 v128, v128
	v_rcp_f32_e32 v174, v174
	v_rcp_f32_e32 v129, v129
	v_rcp_f32_e32 v175, v175
	v_pk_mul_f32 v[122:123], v[118:119], v[126:127]
	v_pk_mul_f32 v[168:169], v[164:165], v[172:173]
	v_pk_mul_f32 v[124:125], v[120:121], v[128:129]
	v_pk_mul_f32 v[170:171], v[166:167], v[174:175]
	v_pk_mul_f32 v[84:85], v[84:85], v[122:123]
	v_pk_mul_f32 v[20:21], v[20:21], v[168:169]
	v_pk_mul_f32 v[86:87], v[86:87], v[124:125]
	v_pk_mul_f32 v[22:23], v[22:23], v[170:171]
	v_cvt_pk_bf16_f32 v190, v84, v85
	v_cvt_pk_bf16_f32 v192, v20, v21
	v_cvt_pk_bf16_f32 v191, v86, v87
	v_cvt_pk_bf16_f32 v193, v22, v23
	global_store_dwordx4 v[162:163], v[190:193], off
	v_lshl_add_u64 v[162:163], v[162:163], 0, s[2:3]
	v_mul_f32_dpp v122, v80, v204 row_ror:1 row_mask:0xf bank_mask:0xf
	v_mul_f32_dpp v168, v16, v208 row_ror:1 row_mask:0xf bank_mask:0xf
	v_mul_f32_dpp v126, v80, v196 row_ror:2 row_mask:0xf bank_mask:0xf
	v_mul_f32_dpp v172, v16, v200 row_ror:2 row_mask:0xf bank_mask:0xf
	v_mul_f32_dpp v123, v81, v205 row_ror:1 row_mask:0xf bank_mask:0xf
	v_mul_f32_dpp v169, v17, v209 row_ror:1 row_mask:0xf bank_mask:0xf
	v_mul_f32_dpp v127, v81, v197 row_ror:2 row_mask:0xf bank_mask:0xf
	v_mul_f32_dpp v173, v17, v201 row_ror:2 row_mask:0xf bank_mask:0xf
	v_mul_f32_dpp v124, v82, v206 row_ror:1 row_mask:0xf bank_mask:0xf
	v_mul_f32_dpp v170, v18, v210 row_ror:1 row_mask:0xf bank_mask:0xf
	v_mul_f32_dpp v128, v82, v198 row_ror:2 row_mask:0xf bank_mask:0xf
	v_mul_f32_dpp v174, v18, v202 row_ror:2 row_mask:0xf bank_mask:0xf
	v_mul_f32_dpp v125, v83, v207 row_ror:1 row_mask:0xf bank_mask:0xf
	v_mul_f32_dpp v171, v19, v211 row_ror:1 row_mask:0xf bank_mask:0xf
	v_mul_f32_dpp v129, v83, v199 row_ror:2 row_mask:0xf bank_mask:0xf
	v_mul_f32_dpp v175, v19, v203 row_ror:2 row_mask:0xf bank_mask:0xf
	v_pk_fma_f32 v[118:119], v[212:213], v[72:73], v[220:221]
	v_pk_fma_f32 v[164:165], v[216:217], v[8:9], v[224:225]
	v_pk_fma_f32 v[120:121], v[214:215], v[74:75], v[222:223]
	v_pk_fma_f32 v[166:167], v[218:219], v[10:11], v[226:227]
	v_mul_f32_dpp v122, v72, v204 row_shr:1 row_mask:0xf bank_mask:0xf
	v_mul_f32_dpp v168, v8, v208 row_shr:1 row_mask:0xf bank_mask:0xf
	v_mul_f32_dpp v126, v72, v196 row_shr:2 row_mask:0xf bank_mask:0xf
	v_mul_f32_dpp v172, v8, v200 row_shr:2 row_mask:0xf bank_mask:0xf
	v_mul_f32_dpp v123, v73, v205 row_shr:1 row_mask:0xf bank_mask:0xf
	v_mul_f32_dpp v169, v9, v209 row_shr:1 row_mask:0xf bank_mask:0xf
	v_mul_f32_dpp v127, v73, v197 row_shr:2 row_mask:0xf bank_mask:0xf
	v_mul_f32_dpp v173, v9, v201 row_shr:2 row_mask:0xf bank_mask:0xf
	v_mul_f32_dpp v124, v74, v206 row_shr:1 row_mask:0xf bank_mask:0xf
	v_mul_f32_dpp v170, v10, v210 row_shr:1 row_mask:0xf bank_mask:0xf
	v_mul_f32_dpp v128, v74, v198 row_shr:2 row_mask:0xf bank_mask:0xf
	v_mul_f32_dpp v174, v10, v202 row_shr:2 row_mask:0xf bank_mask:0xf
	v_mul_f32_dpp v125, v75, v207 row_shr:1 row_mask:0xf bank_mask:0xf
	v_mul_f32_dpp v171, v11, v211 row_shr:1 row_mask:0xf bank_mask:0xf
	v_mul_f32_dpp v129, v75, v199 row_shr:2 row_mask:0xf bank_mask:0xf
	v_mul_f32_dpp v175, v11, v203 row_shr:2 row_mask:0xf bank_mask:0xf
	v_pk_add_f32 v[118:119], v[118:119], v[122:123]
	v_pk_add_f32 v[164:165], v[164:165], v[168:169]
	v_pk_add_f32 v[120:121], v[120:121], v[124:125]
	v_pk_add_f32 v[166:167], v[166:167], v[170:171]
	v_pk_add_f32 v[118:119], v[118:119], v[126:127]
	v_pk_add_f32 v[164:165], v[164:165], v[172:173]
	v_pk_add_f32 v[120:121], v[120:121], v[128:129]
	v_pk_add_f32 v[166:167], v[166:167], v[174:175]
	v_pk_mul_f32 v[122:123], v[118:119], v[118:119]
	v_pk_mul_f32 v[168:169], v[164:165], v[164:165]
	v_pk_mul_f32 v[124:125], v[120:121], v[120:121]
	v_pk_mul_f32 v[170:171], v[166:167], v[166:167]
	v_pk_fma_f32 v[122:123], v[122:123], v[232:233], v[178:179] op_sel_hi:[1,0,0]
	v_pk_fma_f32 v[168:169], v[168:169], v[232:233], v[178:179] op_sel_hi:[1,0,0]
	v_pk_fma_f32 v[124:125], v[124:125], v[232:233], v[178:179] op_sel_hi:[1,0,0]
	v_pk_fma_f32 v[170:171], v[170:171], v[232:233], v[178:179] op_sel_hi:[1,0,0]
	v_pk_mul_f32 v[122:123], v[118:119], v[122:123] neg_lo:[0,1] neg_hi:[0,1]
	v_pk_mul_f32 v[168:169], v[164:165], v[168:169] neg_lo:[0,1] neg_hi:[0,1]
	v_pk_mul_f32 v[124:125], v[120:121], v[124:125] neg_lo:[0,1] neg_hi:[0,1]
	v_pk_mul_f32 v[170:171], v[166:167], v[170:171] neg_lo:[0,1] neg_hi:[0,1]
	v_exp_f32_e32 v126, v122
	v_exp_f32_e32 v172, v168
	v_exp_f32_e32 v127, v123
	v_exp_f32_e32 v173, v169
	v_exp_f32_e32 v128, v124
	v_exp_f32_e32 v174, v170
	v_exp_f32_e32 v129, v125
	v_exp_f32_e32 v175, v171
	v_pk_add_f32 v[126:127], v[126:127], v[248:249] op_sel_hi:[1,0]
	v_pk_add_f32 v[172:173], v[172:173], v[248:249] op_sel_hi:[1,0]
	v_pk_add_f32 v[128:129], v[128:129], v[248:249] op_sel_hi:[1,0]
	v_pk_add_f32 v[174:175], v[174:175], v[248:249] op_sel_hi:[1,0]
	v_rcp_f32_e32 v126, v126
	v_rcp_f32_e32 v172, v172
	v_rcp_f32_e32 v127, v127
	v_rcp_f32_e32 v173, v173
	v_rcp_f32_e32 v128, v128
	v_rcp_f32_e32 v174, v174
	v_rcp_f32_e32 v129, v129
	v_rcp_f32_e32 v175, v175
	v_pk_mul_f32 v[122:123], v[118:119], v[126:127]
	v_pk_mul_f32 v[168:169], v[164:165], v[172:173]
	v_pk_mul_f32 v[124:125], v[120:121], v[128:129]
	v_pk_mul_f32 v[170:171], v[166:167], v[174:175]
	v_pk_mul_f32 v[76:77], v[76:77], v[122:123]
	v_pk_mul_f32 v[12:13], v[12:13], v[168:169]
	v_pk_mul_f32 v[78:79], v[78:79], v[124:125]
	v_pk_mul_f32 v[14:15], v[14:15], v[170:171]
	v_cvt_pk_bf16_f32 v130, v76, v77
	v_cvt_pk_bf16_f32 v132, v12, v13
	v_cvt_pk_bf16_f32 v131, v78, v79
	v_cvt_pk_bf16_f32 v133, v14, v15
	global_store_dwordx4 v[162:163], v[130:133], off
	v_lshl_add_u64 v[162:163], v[162:163], 0, s[2:3]
	v_mul_f32_dpp v122, v72, v204 row_ror:1 row_mask:0xf bank_mask:0xf
	v_mul_f32_dpp v168, v8, v208 row_ror:1 row_mask:0xf bank_mask:0xf
	v_mul_f32_dpp v126, v72, v196 row_ror:2 row_mask:0xf bank_mask:0xf
	v_mul_f32_dpp v172, v8, v200 row_ror:2 row_mask:0xf bank_mask:0xf
	v_mul_f32_dpp v123, v73, v205 row_ror:1 row_mask:0xf bank_mask:0xf
	v_mul_f32_dpp v169, v9, v209 row_ror:1 row_mask:0xf bank_mask:0xf
	v_mul_f32_dpp v127, v73, v197 row_ror:2 row_mask:0xf bank_mask:0xf
	v_mul_f32_dpp v173, v9, v201 row_ror:2 row_mask:0xf bank_mask:0xf
	v_mul_f32_dpp v124, v74, v206 row_ror:1 row_mask:0xf bank_mask:0xf
	v_mul_f32_dpp v170, v10, v210 row_ror:1 row_mask:0xf bank_mask:0xf
	v_mul_f32_dpp v128, v74, v198 row_ror:2 row_mask:0xf bank_mask:0xf
	v_mul_f32_dpp v174, v10, v202 row_ror:2 row_mask:0xf bank_mask:0xf
	v_mul_f32_dpp v125, v75, v207 row_ror:1 row_mask:0xf bank_mask:0xf
	v_mul_f32_dpp v171, v11, v211 row_ror:1 row_mask:0xf bank_mask:0xf
	v_mul_f32_dpp v129, v75, v199 row_ror:2 row_mask:0xf bank_mask:0xf
	v_mul_f32_dpp v175, v11, v203 row_ror:2 row_mask:0xf bank_mask:0xf
	v_pk_fma_f32 v[118:119], v[212:213], v[68:69], v[220:221]
	v_pk_fma_f32 v[164:165], v[216:217], v[4:5], v[224:225]
	v_pk_fma_f32 v[120:121], v[214:215], v[70:71], v[222:223]
	v_pk_fma_f32 v[166:167], v[218:219], v[6:7], v[226:227]
	v_mul_f32_dpp v122, v68, v204 row_shr:1 row_mask:0xf bank_mask:0xf
	v_mul_f32_dpp v168, v4, v208 row_shr:1 row_mask:0xf bank_mask:0xf
	v_mul_f32_dpp v126, v68, v196 row_shr:2 row_mask:0xf bank_mask:0xf
	v_mul_f32_dpp v172, v4, v200 row_shr:2 row_mask:0xf bank_mask:0xf
	v_mul_f32_dpp v123, v69, v205 row_shr:1 row_mask:0xf bank_mask:0xf
	v_mul_f32_dpp v169, v5, v209 row_shr:1 row_mask:0xf bank_mask:0xf
	v_mul_f32_dpp v127, v69, v197 row_shr:2 row_mask:0xf bank_mask:0xf
	v_mul_f32_dpp v173, v5, v201 row_shr:2 row_mask:0xf bank_mask:0xf
	v_mul_f32_dpp v124, v70, v206 row_shr:1 row_mask:0xf bank_mask:0xf
	v_mul_f32_dpp v170, v6, v210 row_shr:1 row_mask:0xf bank_mask:0xf
	v_mul_f32_dpp v128, v70, v198 row_shr:2 row_mask:0xf bank_mask:0xf
	v_mul_f32_dpp v174, v6, v202 row_shr:2 row_mask:0xf bank_mask:0xf
	v_mul_f32_dpp v125, v71, v207 row_shr:1 row_mask:0xf bank_mask:0xf
	v_mul_f32_dpp v171, v7, v211 row_shr:1 row_mask:0xf bank_mask:0xf
	v_mul_f32_dpp v129, v71, v199 row_shr:2 row_mask:0xf bank_mask:0xf
	v_mul_f32_dpp v175, v7, v203 row_shr:2 row_mask:0xf bank_mask:0xf
	v_pk_add_f32 v[118:119], v[118:119], v[122:123]
	v_pk_add_f32 v[164:165], v[164:165], v[168:169]
	v_pk_add_f32 v[120:121], v[120:121], v[124:125]
	v_pk_add_f32 v[166:167], v[166:167], v[170:171]
	v_pk_add_f32 v[118:119], v[118:119], v[126:127]
	v_pk_add_f32 v[164:165], v[164:165], v[172:173]
	v_pk_add_f32 v[120:121], v[120:121], v[128:129]
	v_pk_add_f32 v[166:167], v[166:167], v[174:175]
	v_pk_mul_f32 v[122:123], v[118:119], v[118:119]
	v_pk_mul_f32 v[168:169], v[164:165], v[164:165]
	v_pk_mul_f32 v[124:125], v[120:121], v[120:121]
	v_pk_mul_f32 v[170:171], v[166:167], v[166:167]
	v_pk_fma_f32 v[122:123], v[122:123], v[232:233], v[178:179] op_sel_hi:[1,0,0]
	v_pk_fma_f32 v[168:169], v[168:169], v[232:233], v[178:179] op_sel_hi:[1,0,0]
	v_pk_fma_f32 v[124:125], v[124:125], v[232:233], v[178:179] op_sel_hi:[1,0,0]
	v_pk_fma_f32 v[170:171], v[170:171], v[232:233], v[178:179] op_sel_hi:[1,0,0]
	v_pk_mul_f32 v[122:123], v[118:119], v[122:123] neg_lo:[0,1] neg_hi:[0,1]
	v_pk_mul_f32 v[168:169], v[164:165], v[168:169] neg_lo:[0,1] neg_hi:[0,1]
	v_pk_mul_f32 v[124:125], v[120:121], v[124:125] neg_lo:[0,1] neg_hi:[0,1]
	v_pk_mul_f32 v[170:171], v[166:167], v[170:171] neg_lo:[0,1] neg_hi:[0,1]
	v_exp_f32_e32 v126, v122
	v_exp_f32_e32 v172, v168
	v_exp_f32_e32 v127, v123
	v_exp_f32_e32 v173, v169
	v_exp_f32_e32 v128, v124
	v_exp_f32_e32 v174, v170
	v_exp_f32_e32 v129, v125
	v_exp_f32_e32 v175, v171
	v_pk_add_f32 v[126:127], v[126:127], v[248:249] op_sel_hi:[1,0]
	v_pk_add_f32 v[172:173], v[172:173], v[248:249] op_sel_hi:[1,0]
	v_pk_add_f32 v[128:129], v[128:129], v[248:249] op_sel_hi:[1,0]
	v_pk_add_f32 v[174:175], v[174:175], v[248:249] op_sel_hi:[1,0]
	v_rcp_f32_e32 v126, v126
	v_rcp_f32_e32 v172, v172
	v_rcp_f32_e32 v127, v127
	v_rcp_f32_e32 v173, v173
	v_rcp_f32_e32 v128, v128
	v_rcp_f32_e32 v174, v174
	v_rcp_f32_e32 v129, v129
	v_rcp_f32_e32 v175, v175
	v_pk_mul_f32 v[122:123], v[118:119], v[126:127]
	v_pk_mul_f32 v[168:169], v[164:165], v[172:173]
	v_pk_mul_f32 v[124:125], v[120:121], v[128:129]
	v_pk_mul_f32 v[170:171], v[166:167], v[174:175]
	v_pk_mul_f32 v[64:65], v[64:65], v[122:123]
	v_pk_mul_f32 v[0:1], v[0:1], v[168:169]
	v_pk_mul_f32 v[66:67], v[66:67], v[124:125]
	v_pk_mul_f32 v[2:3], v[2:3], v[170:171]
	v_cvt_pk_bf16_f32 v190, v64, v65
	v_cvt_pk_bf16_f32 v192, v0, v1
	v_cvt_pk_bf16_f32 v191, v66, v67
	v_cvt_pk_bf16_f32 v193, v2, v3
	global_store_dwordx4 v[162:163], v[190:193], off
